# prep: value columns of the 16 tokens touched up front so the serialized per-token load/store chain hits in cache
# speedup vs baseline: 1.0517x; 1.0137x over previous
.LBB0_506:
	v_readlane_b32 s88, v242, 31
	v_readlane_b32 s89, v242, 32
	v_lshlrev_b32_e32 v200, 2, v120
	v_add_u32_e32 v201, 0x1c00, v200
	v_add_u32_e32 v200, 0x1000, v200
	s_or_b32 s90, s67, 0
	s_mul_hi_i32 s91, s90, 0x2a00
	s_mulk_i32 s90, 0x2a00
	s_add_u32 s90, s88, s90
	s_addc_u32 s91, s89, s91
	s_or_b32 s92, s67, 1
	s_mul_hi_i32 s93, s92, 0x2a00
	s_mulk_i32 s92, 0x2a00
	s_add_u32 s92, s88, s92
	s_addc_u32 s93, s89, s93
	global_load_dword v202, v200, s[90:91] offset:2560
	global_load_dword v202, v201, s[90:91] offset:2560
	s_or_b32 s90, s67, 2
	s_mul_hi_i32 s91, s90, 0x2a00
	s_mulk_i32 s90, 0x2a00
	s_add_u32 s90, s88, s90
	s_addc_u32 s91, s89, s91
	global_load_dword v202, v200, s[92:93] offset:2560
	global_load_dword v202, v201, s[92:93] offset:2560
	s_or_b32 s92, s67, 3
	s_mul_hi_i32 s93, s92, 0x2a00
	s_mulk_i32 s92, 0x2a00
	s_add_u32 s92, s88, s92
	s_addc_u32 s93, s89, s93
	global_load_dword v202, v200, s[90:91] offset:2560
	global_load_dword v202, v201, s[90:91] offset:2560
	s_or_b32 s90, s67, 4
	s_mul_hi_i32 s91, s90, 0x2a00
	s_mulk_i32 s90, 0x2a00
	s_add_u32 s90, s88, s90
	s_addc_u32 s91, s89, s91
	global_load_dword v202, v200, s[92:93] offset:2560
	global_load_dword v202, v201, s[92:93] offset:2560
	s_or_b32 s92, s67, 5
	s_mul_hi_i32 s93, s92, 0x2a00
	s_mulk_i32 s92, 0x2a00
	s_add_u32 s92, s88, s92
	s_addc_u32 s93, s89, s93
	global_load_dword v202, v200, s[90:91] offset:2560
	global_load_dword v202, v201, s[90:91] offset:2560
	s_or_b32 s90, s67, 6
	s_mul_hi_i32 s91, s90, 0x2a00
	s_mulk_i32 s90, 0x2a00
	s_add_u32 s90, s88, s90
	s_addc_u32 s91, s89, s91
	global_load_dword v202, v200, s[92:93] offset:2560
	global_load_dword v202, v201, s[92:93] offset:2560
	s_or_b32 s92, s67, 7
	s_mul_hi_i32 s93, s92, 0x2a00
	s_mulk_i32 s92, 0x2a00
	s_add_u32 s92, s88, s92
	s_addc_u32 s93, s89, s93
	global_load_dword v202, v200, s[90:91] offset:2560
	global_load_dword v202, v201, s[90:91] offset:2560
	s_or_b32 s90, s67, 8
	s_mul_hi_i32 s91, s90, 0x2a00
	s_mulk_i32 s90, 0x2a00
	s_add_u32 s90, s88, s90
	s_addc_u32 s91, s89, s91
	global_load_dword v202, v200, s[92:93] offset:2560
	global_load_dword v202, v201, s[92:93] offset:2560
	s_or_b32 s92, s67, 9
	s_mul_hi_i32 s93, s92, 0x2a00
	s_mulk_i32 s92, 0x2a00
	s_add_u32 s92, s88, s92
	s_addc_u32 s93, s89, s93
	global_load_dword v202, v200, s[90:91] offset:2560
	global_load_dword v202, v201, s[90:91] offset:2560
	s_or_b32 s90, s67, 10
	s_mul_hi_i32 s91, s90, 0x2a00
	s_mulk_i32 s90, 0x2a00
	s_add_u32 s90, s88, s90
	s_addc_u32 s91, s89, s91
	global_load_dword v202, v200, s[92:93] offset:2560
	global_load_dword v202, v201, s[92:93] offset:2560
	s_or_b32 s92, s67, 11
	s_mul_hi_i32 s93, s92, 0x2a00
	s_mulk_i32 s92, 0x2a00
	s_add_u32 s92, s88, s92
	s_addc_u32 s93, s89, s93
	global_load_dword v202, v200, s[90:91] offset:2560
	global_load_dword v202, v201, s[90:91] offset:2560
	s_or_b32 s90, s67, 12
	s_mul_hi_i32 s91, s90, 0x2a00
	s_mulk_i32 s90, 0x2a00
	s_add_u32 s90, s88, s90
	s_addc_u32 s91, s89, s91
	global_load_dword v202, v200, s[92:93] offset:2560
	global_load_dword v202, v201, s[92:93] offset:2560
	s_or_b32 s92, s67, 13
	s_mul_hi_i32 s93, s92, 0x2a00
	s_mulk_i32 s92, 0x2a00
	s_add_u32 s92, s88, s92
	s_addc_u32 s93, s89, s93
	global_load_dword v202, v200, s[90:91] offset:2560
	global_load_dword v202, v201, s[90:91] offset:2560
	s_or_b32 s90, s67, 14
	s_mul_hi_i32 s91, s90, 0x2a00
	s_mulk_i32 s90, 0x2a00
	s_add_u32 s90, s88, s90
	s_addc_u32 s91, s89, s91
	global_load_dword v202, v200, s[92:93] offset:2560
	global_load_dword v202, v201, s[92:93] offset:2560
	s_or_b32 s92, s67, 15
	s_mul_hi_i32 s93, s92, 0x2a00
	s_mulk_i32 s92, 0x2a00
	s_add_u32 s92, s88, s92
	s_addc_u32 s93, s89, s93
	global_load_dword v202, v200, s[90:91] offset:2560
	global_load_dword v202, v201, s[90:91] offset:2560
	global_load_dword v202, v200, s[92:93] offset:2560
	global_load_dword v202, v201, s[92:93] offset:2560
	v_lshl_or_b32 v6, v34, 4, v41
	s_lshl_b64 s[0:1], s[0:1], 8
	v_add_u32_e32 v6, v6, v43
	s_add_u32 s0, s0, s55
	v_readlane_b32 s68, v242, 25
	v_ashrrev_i32_e32 v7, 31, v6
	s_addc_u32 s1, s1, 0
	s_mul_i32 s4, s67, 0x2a00
	v_readlane_b32 s74, v242, 31
	v_cvt_pk_bf16_f32 v2, v8, v9
	v_cvt_pk_bf16_f32 v3, v10, v11
	v_cvt_pk_bf16_f32 v4, v16, v17
	v_cvt_pk_bf16_f32 v5, v18, v19
	v_lshl_add_u64 v[0:1], v[6:7], 1, v[0:1]
	s_mul_hi_i32 s5, s67, 0x2a00
	v_readlane_b32 s75, v242, 32
	s_add_u32 s4, s74, s4
	global_store_dwordx4 v[0:1], v[2:5], off
	v_lshlrev_b64 v[0:1], 2, v[120:121]
	s_addc_u32 s5, s75, s5
	v_lshl_add_u64 v[2:3], s[4:5], 0, v[0:1]
	v_add_co_u32_e32 v2, vcc, 0x1000, v2
	v_readlane_b32 s69, v242, 26
	s_nop 0
	v_addc_co_u32_e32 v3, vcc, 0, v3, vcc
	global_load_dword v2, v[2:3], off offset:2560
	v_readlane_b32 s70, v242, 27
	v_readlane_b32 s71, v242, 28
	v_readlane_b32 s72, v242, 29
	v_readlane_b32 s73, v242, 30
	v_readlane_b32 s76, v242, 33
	v_readlane_b32 s77, v242, 34
	v_readlane_b32 s78, v242, 35
	v_readlane_b32 s79, v242, 36
	v_readlane_b32 s80, v242, 37
	v_readlane_b32 s81, v242, 38
	v_readlane_b32 s82, v242, 39
	v_readlane_b32 s83, v242, 40
	v_readlane_b32 s68, v242, 5
	v_cndmask_b32_e64 v3, 0, 1, s[62:63]
	v_readlane_b32 s78, v242, 15
	v_readlane_b32 s79, v242, 16
	v_cmp_ne_u32_e64 s[38:39], 1, v3
	s_andn2_b64 vcc, exec, s[62:63]
	v_lshl_add_u64 v[0:1], s[78:79], 0, v[0:1]
	v_readlane_b32 s69, v242, 6
	v_readlane_b32 s70, v242, 7
	v_readlane_b32 s71, v242, 8
	v_readlane_b32 s72, v242, 9
	v_readlane_b32 s73, v242, 10
	v_readlane_b32 s74, v242, 11
	v_readlane_b32 s75, v242, 12
	v_readlane_b32 s76, v242, 13
	v_readlane_b32 s77, v242, 14
	v_readlane_b32 s80, v242, 17
	v_readlane_b32 s81, v242, 18
	v_readlane_b32 s82, v242, 19
	v_readlane_b32 s83, v242, 20
	s_cbranch_vccnz .LBB0_508
	s_lshl_b64 s[6:7], s[0:1], 10
	v_lshl_add_u64 v[4:5], v[0:1], 0, s[6:7]
	s_waitcnt vmcnt(0)
	global_store_dword v[4:5], v2, off
